# attention K/V DMA: SGPR-base + 32-bit VGPR offset addressing (5 fewer 64-bit VALU adds per tile, 5 narrowed to 32-bit)
# speedup vs baseline: 1.0014x; 1.0014x over previous
.LBB0_597:
	s_waitcnt vmcnt(5)
	s_waitcnt lgkmcnt(0)
	s_barrier
	v_add_u32_e32 v0, s18, v214
	ds_read_b128 v[2:5], v0
	ds_read_b128 v[6:9], v0 offset:8192
	v_xad_u32 v10, v0, 32, 0
	ds_read_b128 v[244:247], v10
	ds_read_b128 v[248:251], v10 offset:8192
	v_xad_u32 v10, v0, 64, 0
	ds_read_b128 v[12:15], v10
	ds_read_b128 v[224:227], v10 offset:8192
	s_add_i32 s19, s19, 1
	s_cmp_ge_u32 s19, s43
	s_cbranch_scc1 .Lattn_nodma_A
	s_add_i32 s44, s18, 0xffff6000
	s_cmp_lg_u32 s18, 0
	s_cselect_b32 s44, s44, 0x14000
	s_add_i32 s44, s44, 0
	s_add_i32 s45, s44, s39
	s_mov_b32 m0, s45
	s_add_i32 s44, s44, s41
	global_load_lds_dwordx4 v210, s[0:1]
	s_add_i32 m0, s45, 0x400
	s_nop 0
	global_load_lds_dwordx4 v212, s[0:1]
	s_add_i32 m0, s44, 0x4000
	s_nop 0
	global_load_lds_dwordx4 v208, s[0:1]
	s_add_i32 m0, s45, 0x6000
	s_nop 0
	global_load_lds_dwordx4 v204, s[0:1]
	s_add_i32 m0, s45, 0x6400
	s_nop 0
	global_load_lds_dwordx4 v206, s[0:1]
.Lattn_nodma_A:
	v_add_u32_e32 v204, s76, v204
	v_add_u32_e32 v206, s76, v206
	v_add_u32_e32 v208, s28, v208
	v_add_u32_e32 v210, s52, v210
	v_add_u32_e32 v212, s52, v212
	s_waitcnt lgkmcnt(4)
	v_mfma_f32_32x32x16_bf16 v[80:95], v[2:5], v[156:159], 0
	v_mfma_f32_32x32x16_bf16 v[96:111], v[6:9], v[156:159], 0
	v_xor_b32_e32 v10, 0x60, v0
	ds_read_b128 v[2:5], v10
	ds_read_b128 v[6:9], v10 offset:8192
	s_waitcnt lgkmcnt(4)
	v_mfma_f32_32x32x16_bf16 v[80:95], v[244:247], v[152:155], v[80:95]
	v_mfma_f32_32x32x16_bf16 v[96:111], v[248:251], v[152:155], v[96:111]
	v_xor_b32_e32 v10, 0x80, v0
	ds_read_b128 v[244:247], v10
	ds_read_b128 v[248:251], v10 offset:8192
	s_waitcnt lgkmcnt(4)
	v_mfma_f32_32x32x16_bf16 v[80:95], v[12:15], v[148:151], v[80:95]
	v_mfma_f32_32x32x16_bf16 v[96:111], v[224:227], v[148:151], v[96:111]
	v_xor_b32_e32 v10, 0xa0, v0
	ds_read_b128 v[12:15], v10
	ds_read_b128 v[224:227], v10 offset:8192
	s_waitcnt lgkmcnt(4)
	v_mfma_f32_32x32x16_bf16 v[80:95], v[2:5], v[144:147], v[80:95]
	v_mfma_f32_32x32x16_bf16 v[96:111], v[6:9], v[144:147], v[96:111]
	v_xor_b32_e32 v10, 0xc0, v0
	ds_read_b128 v[2:5], v10
	ds_read_b128 v[6:9], v10 offset:8192
	s_waitcnt lgkmcnt(4)
	v_mfma_f32_32x32x16_bf16 v[80:95], v[244:247], v[140:143], v[80:95]
	v_mfma_f32_32x32x16_bf16 v[96:111], v[248:251], v[140:143], v[96:111]
	v_xor_b32_e32 v10, 0xe0, v0
	ds_read_b128 v[244:247], v10
	ds_read_b128 v[248:251], v10 offset:8192
	s_waitcnt lgkmcnt(4)
	v_mfma_f32_32x32x16_bf16 v[80:95], v[12:15], v[136:139], v[80:95]
	v_mfma_f32_32x32x16_bf16 v[96:111], v[224:227], v[136:139], v[96:111]
	v_add_u32_e32 v10, s18, v215
	ds_read_b128 v[12:15], v10 offset:16384
	ds_read_b128 v[224:227], v10 offset:20480
	s_waitcnt lgkmcnt(4)
	v_mfma_f32_32x32x16_bf16 v[80:95], v[2:5], v[132:135], v[80:95]
	v_mfma_f32_32x32x16_bf16 v[96:111], v[6:9], v[132:135], v[96:111]
	v_add_u32_e32 v11, s18, v216
	v_xad_u32 v10, v11, 32, 0
	ds_read_b128 v[2:5], v10
	ds_read_b128 v[6:9], v10 offset:4096
	s_waitcnt lgkmcnt(4)
	v_mfma_f32_32x32x16_bf16 v[80:95], v[244:247], v[128:131], v[80:95]
	v_mfma_f32_32x32x16_bf16 v[96:111], v[248:251], v[128:131], v[96:111]
	v_xad_u32 v10, v11, 64, 0
	ds_read_b128 v[244:247], v10
	ds_read_b128 v[248:251], v10 offset:4096
	s_waitcnt lgkmcnt(4)
	v_mfma_f32_32x32x16_bf16 v[80:95], v[12:15], v[124:127], v[80:95]
	v_mfma_f32_32x32x16_bf16 v[96:111], v[224:227], v[124:127], v[96:111]
	v_xor_b32_e32 v10, 0x60, v11
	ds_read_b128 v[12:15], v10
	ds_read_b128 v[224:227], v10 offset:4096
	s_waitcnt lgkmcnt(4)
	v_mfma_f32_32x32x16_bf16 v[80:95], v[2:5], v[120:123], v[80:95]
	v_mfma_f32_32x32x16_bf16 v[96:111], v[6:9], v[120:123], v[96:111]
	v_add_u32_e32 v228, s18, v217
	s_waitcnt lgkmcnt(2)
	v_mfma_f32_32x32x16_bf16 v[80:95], v[244:247], v[116:119], v[80:95]
	v_mfma_f32_32x32x16_bf16 v[96:111], v[248:251], v[116:119], v[96:111]
	ds_read_b128 v[244:247], v228 offset:24576
	ds_read_b128 v[248:251], v228 offset:28672
	s_waitcnt lgkmcnt(2)
	v_mfma_f32_32x32x16_bf16 v[80:95], v[12:15], v[112:115], v[80:95]
	v_mfma_f32_32x32x16_bf16 v[96:111], v[224:227], v[112:115], v[96:111]
	v_add_u32_e32 v229, s18, v218
	v_xad_u32 v243, v229, 32, 0
	v_xad_u32 v252, v229, 64, 0
	v_xor_b32_e32 v253, 0x60, v229
	s_nop 7
	s_nop 0
	v_max_f32_e32 v0, v81, v81
	v_max_f32_e32 v2, v80, v80
	v_max_f32_e32 v0, v2, v0
	v_max3_f32 v0, v0, v82, v83
	v_max3_f32 v0, v0, v84, v85
	v_max3_f32 v0, v0, v86, v87
	v_max3_f32 v0, v0, v88, v89
	v_max3_f32 v0, v0, v90, v91
	v_max3_f32 v0, v0, v92, v93
	v_max3_f32 v0, v0, v94, v95
	v_max3_f32 v0, v0, v96, v97
	v_max3_f32 v0, v0, v98, v99
	v_max3_f32 v0, v0, v100, v101
	v_max3_f32 v0, v0, v102, v103
	v_max3_f32 v0, v0, v104, v105
	v_max3_f32 v0, v0, v106, v107
	v_max3_f32 v0, v0, v108, v109
	v_max3_f32 v0, v0, v110, v111
	ds_bpermute_b32 v2, v219, v0
	s_waitcnt lgkmcnt(0)
	v_max3_f32 v2, v221, v0, v2
	v_sub_f32_e32 v0, v221, v2
	v_exp_f32_e32 v0, v0
	v_cmp_gt_f32_e32 vcc, v2, v221
	s_cbranch_vccz .Lattn_noscale_A
	v_mul_f32_e32 v78, v0, v78
	v_mul_f32_e32 v79, v0, v79
	v_mul_f32_e32 v76, v0, v76
	v_mul_f32_e32 v77, v0, v77
	v_mul_f32_e32 v74, v0, v74
	v_mul_f32_e32 v75, v0, v75
	v_mul_f32_e32 v72, v0, v72
	v_mul_f32_e32 v73, v0, v73
	v_mul_f32_e32 v70, v0, v70
	v_mul_f32_e32 v71, v0, v71
	v_mul_f32_e32 v68, v0, v68
	v_mul_f32_e32 v69, v0, v69
	v_mul_f32_e32 v66, v0, v66
	v_mul_f32_e32 v67, v0, v67
	v_mul_f32_e32 v64, v0, v64
	v_mul_f32_e32 v65, v0, v65
	v_mul_f32_e32 v62, v0, v62
	v_mul_f32_e32 v63, v0, v63
	v_mul_f32_e32 v60, v0, v60
	v_mul_f32_e32 v61, v0, v61
	v_mul_f32_e32 v58, v0, v58
	v_mul_f32_e32 v59, v0, v59
	v_mul_f32_e32 v56, v0, v56
	v_mul_f32_e32 v57, v0, v57
	v_mul_f32_e32 v54, v0, v54
	v_mul_f32_e32 v55, v0, v55
	v_mul_f32_e32 v52, v0, v52
	v_mul_f32_e32 v53, v0, v53
	v_mul_f32_e32 v50, v0, v50
	v_mul_f32_e32 v51, v0, v51
	v_mul_f32_e32 v48, v0, v48
	v_mul_f32_e32 v49, v0, v49
	v_mul_f32_e32 v46, v0, v46
	v_mul_f32_e32 v47, v0, v47
	v_mul_f32_e32 v44, v0, v44
	v_mul_f32_e32 v45, v0, v45
	v_mul_f32_e32 v42, v0, v42
	v_mul_f32_e32 v43, v0, v43
	v_mul_f32_e32 v40, v0, v40
	v_mul_f32_e32 v41, v0, v41
	v_mul_f32_e32 v38, v0, v38
	v_mul_f32_e32 v39, v0, v39
	v_mul_f32_e32 v36, v0, v36
	v_mul_f32_e32 v37, v0, v37
	v_mul_f32_e32 v34, v0, v34
	v_mul_f32_e32 v35, v0, v35
	v_mul_f32_e32 v32, v0, v32
	v_mul_f32_e32 v33, v0, v33
	v_mul_f32_e32 v30, v0, v30
	v_mul_f32_e32 v31, v0, v31
	v_mul_f32_e32 v28, v0, v28
	v_mul_f32_e32 v29, v0, v29
	v_mul_f32_e32 v26, v0, v26
	v_mul_f32_e32 v27, v0, v27
	v_mul_f32_e32 v24, v0, v24
	v_mul_f32_e32 v25, v0, v25
	v_mul_f32_e32 v22, v0, v22
	v_mul_f32_e32 v23, v0, v23
	v_mul_f32_e32 v20, v0, v20
	v_mul_f32_e32 v21, v0, v21
	v_mul_f32_e32 v18, v0, v18
	v_mul_f32_e32 v19, v0, v19
	v_mul_f32_e32 v16, v0, v16
	v_mul_f32_e32 v17, v0, v17
